# code placement: 64-byte alignment of the MLA tile-loop head and the 8 GEMM K-loop heads (p2align 6), rest = v035
# baseline (speedup 1.0000x reference)
; template <class Epi, bool ALIGN_EPI>
; __device__ __forceinline__ void gemm_phase(LAS unsigned char* lds, const Gemm g, const StaticOrder& S, const Epi& E, const int wave_s) {
;     ...
;         float zz1; asm volatile("v_mov_b32 %0, 0" : "=v"(zz1));
; #pragma unroll
;         for (int a = 0; a < 2; ++a)
; #pragma unroll
;             for (int b = 0; b < 2; ++b)
; #pragma unroll
;                 for (int m = 0; m < 4; ++m)
; #pragma unroll
;                     for (int n = 0; n < 2; ++n) acc[a][b][m][n] = (f32x4){zz1, zz1, zz1, zz1};
;         cur = nxt; cA = nA; cB = nB; ++ui;
.LBB0_107:
	s_add_u32 s53, s38, 0x100
	s_addc_u32 s54, s39, 0
	s_add_u32 s38, s40, 0x80
	v_mov_b64_e32 v[6:7], v[2:3]
	v_mov_b64_e32 v[18:19], v[2:3]
	v_mov_b64_e32 v[22:23], v[2:3]
	v_mov_b64_e32 v[34:35], v[2:3]
	v_mov_b64_e32 v[38:39], v[2:3]
	v_mov_b64_e32 v[50:51], v[2:3]
	v_mov_b64_e32 v[54:55], v[2:3]
	v_mov_b64_e32 v[10:11], v[2:3]
	v_mov_b64_e32 v[14:15], v[2:3]
	v_mov_b64_e32 v[26:27], v[2:3]
	v_mov_b64_e32 v[30:31], v[2:3]
	v_mov_b64_e32 v[42:43], v[2:3]
	v_mov_b64_e32 v[46:47], v[2:3]
	v_mov_b64_e32 v[58:59], v[2:3]
	v_mov_b64_e32 v[62:63], v[2:3]
	v_mov_b64_e32 v[66:67], v[2:3]
	v_mov_b64_e32 v[70:71], v[2:3]
	v_mov_b64_e32 v[82:83], v[2:3]
	v_mov_b64_e32 v[86:87], v[2:3]
	v_mov_b64_e32 v[98:99], v[2:3]
	v_mov_b64_e32 v[102:103], v[2:3]
	v_mov_b64_e32 v[114:115], v[2:3]
	v_mov_b64_e32 v[118:119], v[2:3]
	v_mov_b64_e32 v[74:75], v[2:3]
	v_mov_b64_e32 v[78:79], v[2:3]
	v_mov_b64_e32 v[90:91], v[2:3]
	v_mov_b64_e32 v[94:95], v[2:3]
	v_mov_b64_e32 v[106:107], v[2:3]
	v_mov_b64_e32 v[110:111], v[2:3]
	v_mov_b64_e32 v[122:123], v[2:3]
	v_mov_b64_e32 v[126:127], v[2:3]
	s_addc_u32 s39, s41, 0
	s_mov_b32 s40, 0
	v_mov_b64_e32 v[4:5], v[0:1]
	v_mov_b64_e32 v[16:17], v[0:1]
	v_mov_b64_e32 v[20:21], v[0:1]
	v_mov_b64_e32 v[32:33], v[0:1]
	v_mov_b64_e32 v[36:37], v[0:1]
	v_mov_b64_e32 v[48:49], v[0:1]
	v_mov_b64_e32 v[52:53], v[0:1]
	v_mov_b64_e32 v[8:9], v[0:1]
	v_mov_b64_e32 v[12:13], v[0:1]
	v_mov_b64_e32 v[24:25], v[0:1]
	v_mov_b64_e32 v[28:29], v[0:1]
	v_mov_b64_e32 v[40:41], v[0:1]
	v_mov_b64_e32 v[44:45], v[0:1]
	v_mov_b64_e32 v[56:57], v[0:1]
	v_mov_b64_e32 v[60:61], v[0:1]
	v_mov_b64_e32 v[64:65], v[0:1]
	v_mov_b64_e32 v[68:69], v[0:1]
	v_mov_b64_e32 v[80:81], v[0:1]
	v_mov_b64_e32 v[84:85], v[0:1]
	v_mov_b64_e32 v[96:97], v[0:1]
	v_mov_b64_e32 v[100:101], v[0:1]
	v_mov_b64_e32 v[112:113], v[0:1]
	v_mov_b64_e32 v[116:117], v[0:1]
	v_mov_b64_e32 v[72:73], v[0:1]
	v_mov_b64_e32 v[76:77], v[0:1]
	v_mov_b64_e32 v[88:89], v[0:1]
	v_mov_b64_e32 v[92:93], v[0:1]
	v_mov_b64_e32 v[104:105], v[0:1]
	v_mov_b64_e32 v[108:109], v[0:1]
	v_mov_b64_e32 v[120:121], v[0:1]
	v_mov_b64_e32 v[124:125], v[0:1]
	.p2align	6

; template <class Epi, bool ALIGN_EPI>
; __device__ __forceinline__ void gemm_phase(LAS unsigned char* lds, const Gemm g, const StaticOrder& S, const Epi& E, const int wave_s) {
;     ...
;         if (!has_next) break;
;         float zz1; asm volatile("v_mov_b32 %0, 0" : "=v"(zz1));
; #pragma unroll
;         for (int a = 0; a < 2; ++a)
; #pragma unroll
;             for (int b = 0; b < 2; ++b)
; #pragma unroll
;                 for (int m = 0; m < 4; ++m)
; #pragma unroll
;                     for (int n = 0; n < 2; ++n) acc[a][b][m][n] = (f32x4){zz1, zz1, zz1, zz1};
;         cur = nxt; cA = nA; cB = nB; ++ui;
.LBB0_178:
	v_readlane_b32 s0, v254, 57
	v_readlane_b32 s1, v254, 58
	s_andn2_b64 vcc, exec, s[0:1]
	s_cbranch_vccnz .LBB0_181
	s_add_u32 s43, s38, 0x100
	s_addc_u32 s44, s39, 0
	s_add_u32 s0, s40, 0x80
	v_mov_b64_e32 v[44:45], v[54:55]
	v_mov_b64_e32 v[30:31], v[54:55]
	v_mov_b64_e32 v[8:9], v[54:55]
	v_mov_b64_e32 v[0:1], v[54:55]
	v_mov_b64_e32 v[72:73], v[56:57]
	v_mov_b64_e32 v[4:5], v[54:55]
	v_mov_b64_e32 v[76:77], v[56:57]
	v_mov_b64_e32 v[12:13], v[54:55]
	v_mov_b64_e32 v[86:87], v[56:57]
	v_mov_b64_e32 v[22:23], v[54:55]
	v_mov_b64_e32 v[94:95], v[56:57]
	v_mov_b64_e32 v[82:83], v[56:57]
	v_mov_b64_e32 v[16:17], v[54:55]
	v_mov_b64_e32 v[90:91], v[56:57]
	v_mov_b64_e32 v[26:27], v[54:55]
	v_mov_b64_e32 v[110:111], v[56:57]
	v_mov_b64_e32 v[114:115], v[56:57]
	v_mov_b64_e32 v[34:35], v[54:55]
	v_mov_b64_e32 v[118:119], v[56:57]
	v_mov_b64_e32 v[38:39], v[54:55]
	v_mov_b64_e32 v[122:123], v[56:57]
	v_mov_b64_e32 v[48:49], v[54:55]
	v_mov_b64_e32 v[130:131], v[56:57]
	v_mov_b64_e32 v[64:65], v[56:57]
	v_mov_b64_e32 v[138:139], v[56:57]
	v_mov_b64_e32 v[126:127], v[56:57]
	v_mov_b64_e32 v[60:61], v[56:57]
	v_mov_b64_e32 v[134:135], v[56:57]
	v_mov_b64_e32 v[68:69], v[56:57]
	v_mov_b64_e32 v[146:147], v[56:57]
	v_mov_b64_e32 v[150:151], v[56:57]
	s_addc_u32 s1, s41, 0
	s_mov_b32 s38, 0
	v_mov_b64_e32 v[46:47], v[56:57]
	v_mov_b64_e32 v[32:33], v[56:57]
	v_mov_b64_e32 v[10:11], v[56:57]
	v_mov_b64_e32 v[2:3], v[56:57]
	v_mov_b64_e32 v[70:71], v[54:55]
	v_mov_b64_e32 v[6:7], v[56:57]
	v_mov_b64_e32 v[74:75], v[54:55]
	v_mov_b64_e32 v[14:15], v[56:57]
	v_mov_b64_e32 v[84:85], v[54:55]
	v_mov_b64_e32 v[24:25], v[56:57]
	v_mov_b64_e32 v[92:93], v[54:55]
	v_mov_b64_e32 v[80:81], v[54:55]
	v_mov_b64_e32 v[18:19], v[56:57]
	v_mov_b64_e32 v[88:89], v[54:55]
	v_mov_b64_e32 v[28:29], v[56:57]
	v_mov_b64_e32 v[108:109], v[54:55]
	v_mov_b64_e32 v[112:113], v[54:55]
	v_mov_b64_e32 v[36:37], v[56:57]
	v_mov_b64_e32 v[116:117], v[54:55]
	v_mov_b64_e32 v[40:41], v[56:57]
	v_mov_b64_e32 v[120:121], v[54:55]
	v_mov_b64_e32 v[50:51], v[56:57]
	v_mov_b64_e32 v[128:129], v[54:55]
	v_mov_b64_e32 v[62:63], v[54:55]
	v_mov_b64_e32 v[136:137], v[54:55]
	v_mov_b64_e32 v[124:125], v[54:55]
	v_mov_b64_e32 v[58:59], v[54:55]
	v_mov_b64_e32 v[132:133], v[54:55]
	v_mov_b64_e32 v[66:67], v[54:55]
	v_mov_b64_e32 v[144:145], v[54:55]
	v_mov_b64_e32 v[148:149], v[54:55]
	.p2align	6

; template <class Epi, bool ALIGN_EPI>
; __device__ __forceinline__ void gemm_phase(LAS unsigned char* lds, const Gemm g, const StaticOrder& S, const Epi& E, const int wave_s) {
;     ...
;         float zz1; asm volatile("v_mov_b32 %0, 0" : "=v"(zz1));
; #pragma unroll
;         for (int a = 0; a < 2; ++a)
; #pragma unroll
;             for (int b = 0; b < 2; ++b)
; #pragma unroll
;                 for (int m = 0; m < 4; ++m)
; #pragma unroll
;                     for (int n = 0; n < 2; ++n) acc[a][b][m][n] = (f32x4){zz1, zz1, zz1, zz1};
;         cur = nxt; cA = nA; cB = nB; ++ui;
.LBB0_354:
	s_add_u32 s55, s40, 0x100
	s_addc_u32 s56, s41, 0
	s_add_u32 s40, s42, 0x80
	s_waitcnt lgkmcnt(0)
	v_mov_b64_e32 v[6:7], v[2:3]
	v_mov_b64_e32 v[18:19], v[2:3]
	v_mov_b64_e32 v[22:23], v[2:3]
	v_mov_b64_e32 v[34:35], v[2:3]
	v_mov_b64_e32 v[38:39], v[2:3]
	v_mov_b64_e32 v[50:51], v[2:3]
	v_mov_b64_e32 v[54:55], v[2:3]
	v_mov_b64_e32 v[10:11], v[2:3]
	v_mov_b64_e32 v[14:15], v[2:3]
	v_mov_b64_e32 v[26:27], v[2:3]
	v_mov_b64_e32 v[30:31], v[2:3]
	v_mov_b64_e32 v[42:43], v[2:3]
	v_mov_b64_e32 v[46:47], v[2:3]
	v_mov_b64_e32 v[58:59], v[2:3]
	v_mov_b64_e32 v[62:63], v[2:3]
	v_mov_b64_e32 v[66:67], v[2:3]
	v_mov_b64_e32 v[70:71], v[2:3]
	v_mov_b64_e32 v[82:83], v[2:3]
	v_mov_b64_e32 v[86:87], v[2:3]
	v_mov_b64_e32 v[98:99], v[2:3]
	v_mov_b64_e32 v[102:103], v[2:3]
	v_mov_b64_e32 v[114:115], v[2:3]
	v_mov_b64_e32 v[118:119], v[2:3]
	v_mov_b64_e32 v[74:75], v[2:3]
	v_mov_b64_e32 v[78:79], v[2:3]
	v_mov_b64_e32 v[90:91], v[2:3]
	v_mov_b64_e32 v[94:95], v[2:3]
	v_mov_b64_e32 v[106:107], v[2:3]
	v_mov_b64_e32 v[110:111], v[2:3]
	v_mov_b64_e32 v[122:123], v[2:3]
	v_mov_b64_e32 v[126:127], v[2:3]
	s_addc_u32 s41, s43, 0
	s_mov_b32 s42, 0
	v_mov_b64_e32 v[4:5], v[0:1]
	v_mov_b64_e32 v[16:17], v[0:1]
	v_mov_b64_e32 v[20:21], v[0:1]
	v_mov_b64_e32 v[32:33], v[0:1]
	v_mov_b64_e32 v[36:37], v[0:1]
	v_mov_b64_e32 v[48:49], v[0:1]
	v_mov_b64_e32 v[52:53], v[0:1]
	v_mov_b64_e32 v[8:9], v[0:1]
	v_mov_b64_e32 v[12:13], v[0:1]
	v_mov_b64_e32 v[24:25], v[0:1]
	v_mov_b64_e32 v[28:29], v[0:1]
	v_mov_b64_e32 v[40:41], v[0:1]
	v_mov_b64_e32 v[44:45], v[0:1]
	v_mov_b64_e32 v[56:57], v[0:1]
	v_mov_b64_e32 v[60:61], v[0:1]
	v_mov_b64_e32 v[64:65], v[0:1]
	v_mov_b64_e32 v[68:69], v[0:1]
	v_mov_b64_e32 v[80:81], v[0:1]
	v_mov_b64_e32 v[84:85], v[0:1]
	v_mov_b64_e32 v[96:97], v[0:1]
	v_mov_b64_e32 v[100:101], v[0:1]
	v_mov_b64_e32 v[112:113], v[0:1]
	v_mov_b64_e32 v[116:117], v[0:1]
	v_mov_b64_e32 v[72:73], v[0:1]
	v_mov_b64_e32 v[76:77], v[0:1]
	v_mov_b64_e32 v[88:89], v[0:1]
	v_mov_b64_e32 v[92:93], v[0:1]
	v_mov_b64_e32 v[104:105], v[0:1]
	v_mov_b64_e32 v[108:109], v[0:1]
	v_mov_b64_e32 v[120:121], v[0:1]
	v_mov_b64_e32 v[124:125], v[0:1]
	.p2align	6

; #define LAS __attribute__((address_space(3)))
; #define GAS __attribute__((address_space(1)))
; template <bool MLA, int ldq, int ldk, int ldo, bool GQA4 = false> ...
;     ...
;     int tid_ = tid_now(wave_s); asm volatile("" : "+v"(tid_));
;     const int tid = tid_, wid = tid >> 6, lane = tid & 63, r32 = lane & 31, hi = lane >> 5;
;     const int widu = __builtin_amdgcn_readfirstlane(wid);
;     LAS unsigned char* ldsl = (LAS unsigned char*)lds;
;     char* V_lds = lds + OFF_V; char* K_lds = lds + OFF_K; char* Kr_lds = lds + OFF_KRL;
;     float* ws = (float*)(lds + OFF_WSF) + wid * 64; float* li_l = ws; float* al_l = ws + 32;
;     const float* bt = (const float*)(lds + OFF_BT) + (GQA4 ? (wid >> 1) * 768 : 0);
;     float m_reg = MLA ? -1e30f : sink, l_reg = MLA ? 0.f : 1.f; f32x16 o[4] = {}; bf16x8 qr[NQ];
;     const bf16_t* Qw = GQA4 ? Qb + (long)((wid & 1) * QBLK + r32) * ldq + (wid >> 1) * 128 + hi * 8 : Qb + (long)(wid * QBLK + r32) * ldq + hi * 8;
; #pragma unroll
;     for (int d0 = 0; d0 < NQ; ++d0) qr[d0] = *(const GAS bf16x8*)(Qw + d0 * 16);
;     int koff, voff, kroff;
;     { const int b = wid * 1024 + lane * 16;
;       { const int row = b >> 8, cB = (b & 255) ^ ((row & 7) << 4); koff = row * ldk + (cB >> 1); }
;       { const int sub = b >> 9, kk = (sub >> 2) * 8 + ((b & 511) >> 6), c = (sub & 3) * 32 + ((b & 63) >> 1), k = (kk & ~0xC) | ((kk & 4) << 1) | ((kk & 8) >> 1); voff = k * ldk + c; }
;       { const int row = b >> 7, cB = (b & 127) ^ ((row & 7) << 4); kroff = row * ROPE + (cB >> 1); } }
;     const int vb0 = (int)(uintptr_t)V_lds + v_rd_base(lane);
;     const int relq = rel0 - (GQA4 ? (wid & 1) : wid) * QBLK - r32;
;     ...
;     f32x16 pA0, pA1, pB0, pB1; float mnA, mnB, alA, alB, ps0; bf16x8 pa0, pa1, pa2, pa3;
;     f32x16 negm = f32x16{}; if constexpr (MLA) { m_reg = 0.f; asm volatile("" : "+v"(negm)); }
;     ...
;     int sp = 2, sc = 0, sn = 1;
;     DMA_K(0, 0); DMA_K(1, 1); DMA_V(0, 0); DMA_K(2, 2); DMA_V(1, 1);
;     WAITBAR_G2();
; __global__ void __launch_bounds__(NWAVES * 64, 2) mk_fwd(Args a) {
;     ...
;             for (int u = vcu; u < NU; u += G) { const int bh = u / NQB, qb = u % NQB, b = bh / NH, h = bh % NH; const size_t row0 = (size_t)b * SEQ;
;                 att::attn_unit<true, QW, KVW, DM>(Q + (row0 + (size_t)qb * 256) * QW + h * 192, KV + row0 * KVW + h * 256, KV + row0 * KVW + h * 256 + 128, KR + row0 * ROPE,
.LBB0_458:
	s_ashr_i32 s1, s17, 31
	s_lshr_b32 s0, s1, 26
	s_add_i32 s0, s17, s0
	s_lshr_b32 s1, s1, 23
	s_ashr_i32 s6, s0, 6
	s_add_i32 s1, s17, s1
	s_ashr_i32 s10, s1, 9
	s_lshr_b32 s1, s6, 29
	s_andn2_b32 s0, s0, 63
	s_add_i32 s1, s6, s1
	s_sub_i32 s0, s17, s0
	s_and_b32 s1, s1, -8
	s_sub_i32 s18, s6, s1
	s_ashr_i32 s11, s10, 31
	s_ashr_i32 s1, s0, 31
	s_lshl_b64 s[6:7], s[10:11], 14
	s_lshl_b64 s[0:1], s[0:1], 8
	s_add_u32 s0, s6, s0
	s_addc_u32 s1, s7, s1
	s_mul_i32 s6, s1, 0xc00
	s_mul_hi_u32 s7, s0, 0xc00
	s_add_i32 s7, s7, s6
	s_mul_i32 s6, s0, 0xc00
	v_mov_b32 v0, 0
	s_add_u32 s8, s46, s6
	s_mul_i32 s6, s18, 0xc0
	v_mbcnt_lo_u32_b32 v0, -1, v0
	s_addc_u32 s9, s47, s7
	s_ashr_i32 s7, s6, 31
	v_mbcnt_hi_u32_b32 v0, -1, v0
	s_lshl_b64 s[6:7], s[6:7], 1
	v_add_u32_e32 v8, s95, v0
	s_add_u32 s20, s8, s6
	s_addc_u32 s21, s9, s7
	v_ashrrev_i32_e32 v2, 6, v8
	v_and_b32_e32 v187, 31, v8
	v_lshlrev_b32_e32 v192, 5, v2
	v_bfe_u32 v250, v8, 5, 1
	s_waitcnt lgkmcnt(0)
	v_or_b32_e32 v3, v192, v187
	v_mov_b64_e32 v[0:1], s[20:21]
	s_movk_i32 s19, 0xc00
	v_mad_i64_i32 v[0:1], s[20:21], v3, s19, v[0:1]
	v_lshlrev_b32_e32 v184, 4, v250
	v_lshl_add_u64 v[0:1], v[0:1], 0, v[184:185]
	global_load_dwordx4 v[172:175], v[0:1], off
	global_load_dwordx4 v[168:171], v[0:1], off offset:32
	global_load_dwordx4 v[164:167], v[0:1], off offset:64
	global_load_dwordx4 v[160:163], v[0:1], off offset:96
	global_load_dwordx4 v[156:159], v[0:1], off offset:128
	global_load_dwordx4 v[152:155], v[0:1], off offset:160
	global_load_dwordx4 v[148:151], v[0:1], off offset:192
	global_load_dwordx4 v[144:147], v[0:1], off offset:224
	global_load_dwordx4 v[140:143], v[0:1], off offset:256
	global_load_dwordx4 v[136:139], v[0:1], off offset:288
	global_load_dwordx4 v[132:135], v[0:1], off offset:320
	global_load_dwordx4 v[128:131], v[0:1], off offset:352
	v_and_b32_e32 v58, 63, v8
	s_lshl_b64 s[6:7], s[10:11], 26
	v_lshlrev_b32_e32 v9, 4, v58
	s_add_u32 s12, s40, s6
	v_lshl_or_b32 v1, v2, 10, v9
	s_addc_u32 s13, s41, s7
	s_lshl_b32 s8, s18, 8
	v_ashrrev_i32_e32 v0, 8, v1
	s_ashr_i32 s9, s8, 31
	v_readfirstlane_b32 s19, v2
	v_and_b32_e32 v2, 0xf0, v9
	v_lshlrev_b32_e32 v3, 4, v0
	s_movk_i32 s21, 0x70
	s_lshl_b64 s[8:9], s[8:9], 1
	v_bitop3_b32 v2, v3, v2, s21 bitop3:0x6c
	v_lshrrev_b32_e32 v3, 4, v1
	s_add_u32 s12, s12, s8
	v_lshrrev_b32_e32 v2, 1, v2
	v_and_b32_e32 v60, 0x60, v3
	v_lshrrev_b32_e32 v3, 1, v8
	s_addc_u32 s13, s13, s9
	s_lshl_b64 s[10:11], s[10:11], 21
	v_lshl_or_b32 v0, v0, 11, v2
	v_ashrrev_i32_e32 v2, 4, v8
	v_and_b32_e32 v3, 8, v3
	v_ashrrev_i32_e32 v1, 7, v1
	s_add_u32 s14, s4, s10
	v_and_or_b32 v63, v2, -16, v3
	v_xor_b32_e32 v3, v1, v8
	s_addc_u32 s15, s16, s11
	s_add_i32 s28, 0, 0x1e000
	v_lshrrev_b32_e32 v4, 1, v2
	v_lshlrev_b32_e32 v1, 6, v1
	v_lshlrev_b32_e32 v3, 3, v3
	v_and_b32_e32 v62, 4, v4
	v_and_or_b32 v4, v3, 56, v1
	s_cmp_lg_u32 0, -1
	v_ashrrev_i32_e32 v1, 31, v0
	s_cselect_b32 s29, 0, 0
	v_lshlrev_b64 v[48:49], 1, v[0:1]
	s_lshl_b32 s19, s19, 10
	v_lshl_add_u64 v[52:53], s[12:13], 0, v[48:49]
	s_add_i32 s20, s19, 0
	s_mov_b64 s[24:25], 0x20000
	v_ashrrev_i32_e32 v5, 31, v4
	v_bfe_u32 v59, v8, 2, 2
	v_mov_b32_e32 v16, v185
	v_mov_b32_e32 v17, v185
	v_mov_b32_e32 v18, v185
	v_mov_b32_e32 v19, v185
	v_mov_b32_e32 v20, v185
	v_mov_b32_e32 v21, v185
	v_mov_b32_e32 v22, v185
	v_mov_b32_e32 v23, v185
	v_mov_b32_e32 v24, v185
	v_mov_b32_e32 v25, v185
	v_mov_b32_e32 v26, v185
	v_mov_b32_e32 v27, v185
	v_mov_b32_e32 v28, v185
	v_mov_b32_e32 v29, v185
	v_mov_b32_e32 v30, v185
	v_mov_b32_e32 v31, v185
	s_mov_b32 m0, s20
	v_lshl_add_u64 v[0:1], v[52:53], 0, s[24:25]
	s_add_i32 s25, s20, 0x2000
	v_lshlrev_b64 v[50:51], 1, v[4:5]
	v_lshlrev_b32_e32 v10, 3, v58
	v_or3_b32 v2, v63, v59, v62
	global_load_lds_dwordx4 v[52:53], off
	s_mov_b32 m0, s25
	v_lshl_add_u64 v[54:55], s[14:15], 0, v[50:51]
	s_add_i32 s14, s20, 0xc000
	v_and_b32_e32 v61, 24, v10
	v_lshlrev_b32_e32 v2, 11, v2
	global_load_lds_dwordx4 v[0:1], off
	s_mov_b32 m0, s14
	s_mov_b64 s[36:37], 0x40000
	v_or3_b32 v2, v2, v60, v61
	global_load_lds_dwordx4 v[54:55], off
	v_lshl_add_u64 v[0:1], v[52:53], 0, s[36:37]
	s_add_i32 m0, s20, 0x4000
	s_mov_b64 s[36:37], 0x60000
	global_load_lds_dwordx4 v[0:1], off
	v_lshl_add_u64 v[0:1], v[52:53], 0, s[36:37]
	s_add_i32 m0, s20, 0x6000
	s_mov_b64 s[36:37], 0x2000
	v_ashrrev_i32_e32 v3, 31, v2
	global_load_lds_dwordx4 v[0:1], off
	v_lshl_add_u64 v[0:1], v[54:55], 0, s[36:37]
	s_add_i32 m0, s20, 0xe000
	v_lshl_add_u64 v[56:57], v[2:3], 1, s[12:13]
	s_mov_b64 s[12:13], 0x100
	global_load_lds_dwordx4 v[0:1], off
	v_lshl_add_u64 v[0:1], v[56:57], 0, s[12:13]
	s_add_i32 s12, s20, 0x12000
	s_mov_b32 m0, s12
	s_mov_b64 s[36:37], 0x20100
	global_load_lds_dwordx4 v[0:1], off
	v_lshl_add_u64 v[0:1], v[56:57], 0, s[36:37]
	s_add_i32 m0, s20, 0x14000
	s_mov_b64 s[36:37], 0x80000
	global_load_lds_dwordx4 v[0:1], off
	v_lshl_add_u64 v[0:1], v[52:53], 0, s[36:37]
	s_add_i32 m0, s20, 0x8000
	s_mov_b64 s[36:37], 0xa0000
	global_load_lds_dwordx4 v[0:1], off
	v_lshl_add_u64 v[0:1], v[52:53], 0, s[36:37]
	s_add_i32 m0, s20, 0xa000
	s_mov_b64 s[36:37], 0x4000
	global_load_lds_dwordx4 v[0:1], off
	v_lshl_add_u64 v[0:1], v[54:55], 0, s[36:37]
	s_add_i32 m0, s20, 0x10000
	s_mov_b64 s[36:37], 0x40100
	global_load_lds_dwordx4 v[0:1], off
	v_lshl_add_u64 v[0:1], v[56:57], 0, s[36:37]
	s_add_i32 m0, s20, 0x16000
	s_mov_b64 s[36:37], 0x60100
	global_load_lds_dwordx4 v[0:1], off
	v_lshl_add_u64 v[0:1], v[56:57], 0, s[36:37]
	s_add_i32 m0, s20, 0x18000
	v_lshlrev_b32_e32 v218, 8, v187
	v_lshlrev_b32_e32 v11, 4, v8
	global_load_lds_dwordx4 v[0:1], off
	v_add_u32_e32 v12, 0, v218
	v_bitop3_b32 v217, v184, v11, s21 bitop3:0x78
	s_waitcnt vmcnt(10) lgkmcnt(0)
	s_barrier
; #define FIX(P0, P1, t) do { if constexpr (!MLA) swa_fix(P0, P1, bt, relq + (t) * KVBLK, hi); } while (0)
; #define PSM(P0, P1, MN, AL, FIRST) do { if constexpr (MLA) partialSM_mla<FIRST>(P0, P1, m_reg, negm, AL); else partialSM<false>(P0, P1, m_reg, MN, AL); pack_p0(P0, pa0, pa1, ps0); } while (0)
; template <bool MLA>
; __device__ __forceinline__ void qkt(f32x16& p0, f32x16& p1, const char* Ks, const char* Krs, const bf16x8* qr, int r32, int hi, const f32x16& cinit) {
;     p0 = cinit; p1 = cinit;
; #pragma unroll
;     for (int d0 = 0; d0 < 8; ++d0) { const int cb = (d0 * 16 + hi * 8) * 2;
;         const bf16x8 b0 = *reinterpret_cast<const bf16x8*>(Ks + KSWZ(r32, cb));
;         const bf16x8 b1 = *reinterpret_cast<const bf16x8*>(Ks + KSWZ(32 + r32, cb));
;         p0 = __builtin_amdgcn_mfma_f32_32x32x16_bf16(b0, qr[d0], p0, 0, 0, 0);
;         p1 = __builtin_amdgcn_mfma_f32_32x32x16_bf16(b1, qr[d0], p1, 0, 0, 0); }
;     if constexpr (MLA) {
; #pragma unroll
;         for (int d0 = 0; d0 < 4; ++d0) { const int cb = (d0 * 16 + hi * 8) * 2;
;             const bf16x8 b0 = *reinterpret_cast<const bf16x8*>(Krs + KRSWZ(r32, cb));
;             const bf16x8 b1 = *reinterpret_cast<const bf16x8*>(Krs + KRSWZ(32 + r32, cb));
;             p0 = __builtin_amdgcn_mfma_f32_32x32x16_bf16(b0, qr[8 + d0], p0, 0, 0, 0);
;             p1 = __builtin_amdgcn_mfma_f32_32x32x16_bf16(b1, qr[8 + d0], p1, 0, 0, 0); }
;     }
; }
; template <bool MLA, int ldq, int ldk, int ldo, bool GQA4 = false> ...
;     ...
;     qkt<MLA>(pA0, pA1, K_lds, Kr_lds, qr, r32, hi, negm); FIX(pA0, pA1, 0); PSM(pA0, pA1, mnA, alA, true);
	v_add_u32_e32 v4, v12, v217
	ds_read_b128 v[0:3], v4
	ds_read_b128 v[4:7], v4 offset:8192
	s_waitcnt vmcnt(0) lgkmcnt(0)
	v_mfma_f32_32x32x16_bf16 v[32:47], v[0:3], v[172:175], v[16:31]
	v_and_b32_e32 v96, 0x70, v11
	v_bitop3_b32 v216, v184, v96, 32 bitop3:0x36
	v_bitop3_b32 v215, v184, v96, 64 bitop3:0x36
	v_bitop3_b32 v214, v184, v96, s91 bitop3:0x36
	s_movk_i32 s13, 0x80
	v_bitop3_b32 v223, v184, v96, s13 bitop3:0x36
	s_movk_i32 s13, 0xa0
	v_mfma_f32_32x32x16_bf16 v[16:31], v[4:7], v[172:175], v[16:31]
	v_add_u32_e32 v4, v12, v216
	ds_read_b128 v[0:3], v4
	ds_read_b128 v[4:7], v4 offset:8192
	v_bitop3_b32 v222, v184, v96, s13 bitop3:0x36
	s_movk_i32 s15, 0xc0
	v_bitop3_b32 v221, v184, v96, s15 bitop3:0x36
	s_movk_i32 s13, 0xe0
	v_bitop3_b32 v220, v184, v96, s13 bitop3:0x36
	s_waitcnt lgkmcnt(1)
	v_mfma_f32_32x32x16_bf16 v[32:47], v[0:3], v[168:171], v[32:47]
	v_lshlrev_b32_e32 v219, 7, v187
	v_sub_u32_e32 v11, v12, v219
	v_add_u32_e32 v14, v11, v214
	s_mov_b64 s[36:37], 0xc0000
	s_mov_b32 m0, s20
	s_add_i32 s29, s29, 0x12000
	v_mov_b32_e32 v15, v185
	s_waitcnt lgkmcnt(0)
	v_mfma_f32_32x32x16_bf16 v[16:31], v[4:7], v[168:171], v[16:31]
	v_add_u32_e32 v4, v12, v215
	ds_read_b128 v[0:3], v4
	ds_read_b128 v[4:7], v4 offset:8192
	v_or_b32_e32 v97, 32, v184
	v_bitop3_b32 v224, v184, v218, v96 bitop3:0xde
	v_bitop3_b32 v225, v97, v218, v96 bitop3:0xde
	v_lshl_add_u64 v[194:195], s[10:11], 0, v[50:51]
	s_mov_b32 s24, 1
	s_waitcnt lgkmcnt(1)
	v_mfma_f32_32x32x16_bf16 v[32:47], v[0:3], v[164:167], v[32:47]
	s_mov_b32 s13, 2
	s_mov_b32 s21, 0
	v_bitop3_b32 v232, v184, v219, v96 bitop3:0xde
	v_bitop3_b32 v233, v97, v219, v96 bitop3:0xde
	v_sub_u32_e32 v236, v224, v219
	v_sub_u32_e32 v237, v225, v219
	v_mov_b32_e32 v212, 0
	s_waitcnt lgkmcnt(0)
	v_mfma_f32_32x32x16_bf16 v[16:31], v[4:7], v[164:167], v[16:31]
	v_add_u32_e32 v4, v12, v214
	ds_read_b128 v[0:3], v4
	ds_read_b128 v[4:7], v4 offset:8192
	v_mov_b32_e32 v240, 1.0
	s_waitcnt lgkmcnt(1)
	v_mfma_f32_32x32x16_bf16 v[32:47], v[0:3], v[160:163], v[32:47]
	s_waitcnt lgkmcnt(0)
	v_mfma_f32_32x32x16_bf16 v[16:31], v[4:7], v[160:163], v[16:31]
	v_add_u32_e32 v4, v12, v223
	ds_read_b128 v[0:3], v4
	ds_read_b128 v[4:7], v4 offset:8192
	s_waitcnt lgkmcnt(1)
	v_mfma_f32_32x32x16_bf16 v[32:47], v[0:3], v[156:159], v[32:47]
	s_waitcnt lgkmcnt(0)
	v_mfma_f32_32x32x16_bf16 v[16:31], v[4:7], v[156:159], v[16:31]
	v_add_u32_e32 v4, v12, v222
	ds_read_b128 v[0:3], v4
	ds_read_b128 v[4:7], v4 offset:8192
	s_waitcnt lgkmcnt(1)
	v_mfma_f32_32x32x16_bf16 v[32:47], v[0:3], v[152:155], v[32:47]
	s_waitcnt lgkmcnt(0)
	v_mfma_f32_32x32x16_bf16 v[16:31], v[4:7], v[152:155], v[16:31]
	v_add_u32_e32 v4, v12, v221
	ds_read_b128 v[0:3], v4
	ds_read_b128 v[4:7], v4 offset:8192
	s_waitcnt lgkmcnt(1)
	v_mfma_f32_32x32x16_bf16 v[32:47], v[0:3], v[148:151], v[32:47]
	s_waitcnt lgkmcnt(0)
	v_mfma_f32_32x32x16_bf16 v[16:31], v[4:7], v[148:151], v[16:31]
	v_add_u32_e32 v4, v12, v220
	ds_read_b128 v[0:3], v4
	ds_read_b128 v[4:7], v4 offset:8192
	v_add_u32_e32 v12, v11, v215
	s_waitcnt lgkmcnt(1)
	v_mfma_f32_32x32x16_bf16 v[32:47], v[0:3], v[144:147], v[32:47]
	s_waitcnt lgkmcnt(0)
	v_mfma_f32_32x32x16_bf16 v[16:31], v[4:7], v[144:147], v[16:31]
	v_add_u32_e32 v4, v11, v217
	ds_read_b128 v[0:3], v4 offset:49152
	ds_read_b128 v[4:7], v4 offset:53248
	s_waitcnt lgkmcnt(1)
	v_mfma_f32_32x32x16_bf16 v[32:47], v[0:3], v[140:143], v[32:47]
	s_waitcnt lgkmcnt(0)
	v_mfma_f32_32x32x16_bf16 v[16:31], v[4:7], v[140:143], v[16:31]
	v_add_u32_e32 v4, v11, v216
	ds_read_b128 v[0:3], v4 offset:49152
	ds_read_b128 v[4:7], v4 offset:53248
	ds_read_b128 v[64:67], v14 offset:53248
	s_waitcnt lgkmcnt(2)
	v_mfma_f32_32x32x16_bf16 v[32:47], v[0:3], v[136:139], v[32:47]
	v_and_b32_e32 v0, 0x3fffffc0, v8
	v_lshl_add_u32 v193, v0, 2, s28
	ds_read_b128 v[0:3], v12 offset:49152
	v_lshlrev_b32_e32 v8, 1, v8
	v_lshl_add_u32 v211, v187, 2, v193
	s_waitcnt lgkmcnt(2)
	v_mfma_f32_32x32x16_bf16 v[16:31], v[4:7], v[136:139], v[16:31]
	v_and_b32_e32 v4, 32, v8
	v_and_or_b32 v4, v9, s15, v4
	v_and_b32_e32 v5, 0x100, v10
	v_or3_b32 v8, v4, v5, v61
	ds_read_b128 v[4:7], v12 offset:53248
	ds_read_b128 v[10:13], v14 offset:49152
	v_mov_b32_e32 v14, v185
	s_waitcnt lgkmcnt(2)
	v_mfma_f32_32x32x16_bf16 v[32:47], v[0:3], v[132:135], v[32:47]
	v_add_u32_e32 v210, s29, v8
	v_mov_b32_e32 v0, v185
	v_mov_b32_e32 v1, v185
	v_mov_b32_e32 v2, v185
	v_mov_b32_e32 v3, v185
	v_mov_b32_e32 v8, v185
	v_mov_b32_e32 v9, v185
	s_waitcnt lgkmcnt(1)
	v_mfma_f32_32x32x16_bf16 v[16:31], v[4:7], v[132:135], v[16:31]
	v_mov_b32_e32 v4, v185
	v_mov_b32_e32 v5, v185
	v_mov_b32_e32 v6, v185
	v_mov_b32_e32 v7, v185
	s_waitcnt lgkmcnt(0)
; #define DMA_V(t, s) do { const bf16_t* vp_ = Vh + (long)(t) * KVBLK * ldk; \
;     __builtin_amdgcn_global_load_lds((const unsigned*)(vp_ + voff), (LAS unsigned*)(ldsl + OFF_V + (s) * SHM_V + widu * 1024), 16, 0, 0); \
;     __builtin_amdgcn_global_load_lds((const unsigned*)(vp_ + 32 * ldk + voff), (LAS unsigned*)(ldsl + OFF_V + (s) * SHM_V + 8192 + widu * 1024), 16, 0, 0); } while (0)
; #define WAITBAR_G1() do { if constexpr (MLA) asm volatile("s_waitcnt vmcnt(5) lgkmcnt(0)\n\ts_barrier" ::: "memory"); else asm volatile("s_waitcnt vmcnt(4) lgkmcnt(0)\n\ts_barrier" ::: "memory"); } while (0)
; #define WAITBAR_G2() do { if constexpr (MLA) asm volatile("s_waitcnt vmcnt(10) lgkmcnt(0)\n\ts_barrier" ::: "memory"); else asm volatile("s_waitcnt vmcnt(8) lgkmcnt(0)\n\ts_barrier" ::: "memory"); } while (0)
; #define FIX(P0, P1, t) do { if constexpr (!MLA) swa_fix(P0, P1, bt, relq + (t) * KVBLK, hi); } while (0)
; #define ROT() do { sp = sc; sc = sn; sn = (sn == 2) ? 0 : sn + 1; } while (0)
; template <bool FIRST>
; __device__ __forceinline__ void partialSM_mla(f32x16& p0, f32x16& p1, float& m_reg, f32x16& negm, float& alpha) {
;     constexpr float THRL = THR * LOG2E;
;     float pmax = p0[0];
; #pragma unroll
;     for (int r = 1; r < 16; ++r) pmax = fmaxf(pmax, p0[r]);
; #pragma unroll
;     for (int r = 0; r < 16; ++r) pmax = fmaxf(pmax, p1[r]);
;     { auto rr = __builtin_amdgcn_permlane32_swap(__float_as_uint(pmax), __float_as_uint(pmax), false, false);
;       pmax = fmaxf(__uint_as_float(rr[0]), __uint_as_float(rr[1])); }
;     if (!FIRST && __builtin_expect(__all(pmax <= THRL), 1)) { alpha = 1.f; }
;     else { const float dl = FIRST ? pmax : fmaxf(pmax, 0.f); m_reg += dl; alpha = FIRST ? 1.f : __builtin_amdgcn_exp2f(-dl);
; #pragma unroll
;         for (int r = 0; r < 16; ++r) { p0[r] -= dl; p1[r] -= dl; }
; #pragma unroll
;         for (int r = 0; r < 16; ++r) negm[r] = -m_reg;
;         asm volatile("" : "+v"(negm)); }
; #pragma unroll
;     for (int r = 0; r < 16; ++r) p0[r] = __builtin_amdgcn_exp2f(p0[r]);
; }
; template <bool MLA, int ldq, int ldk, int ldo, bool GQA4 = false> ...
;     ...
;     DMA_K(0, 0); DMA_K(1, 1); DMA_V(0, 0); DMA_K(2, 2); DMA_V(1, 1);
;     WAITBAR_G2();
;     qkt<MLA>(pA0, pA1, K_lds, Kr_lds, qr, r32, hi, negm); FIX(pA0, pA1, 0); PSM(pA0, pA1, mnA, alA, true);
;     WAITBAR_G1();
;     DMA_K(3, 0); DMA_V(2, 2);
;     ROT();
	v_mfma_f32_32x32x16_bf16 v[32:47], v[10:13], v[128:131], v[32:47]
	v_mov_b32_e32 v10, v185
	v_mov_b32_e32 v11, v185
	v_mov_b32_e32 v12, v185
	v_mov_b32_e32 v13, v185
	v_mfma_f32_32x32x16_bf16 v[16:31], v[64:67], v[128:131], v[16:31]
	s_nop 6
	v_max_f32_e32 v64, v33, v33
	v_max_f32_e32 v65, v32, v32
	v_max_f32_e32 v64, v65, v64
	v_max3_f32 v64, v64, v34, v35
	v_max3_f32 v64, v64, v36, v37
	v_max3_f32 v64, v64, v38, v39
	v_max3_f32 v64, v64, v40, v41
	v_max3_f32 v64, v64, v42, v43
	v_max3_f32 v64, v64, v44, v45
	v_max3_f32 v64, v64, v46, v47
	v_max3_f32 v64, v64, v16, v17
	v_max3_f32 v64, v64, v18, v19
	v_max3_f32 v64, v64, v20, v21
	v_max3_f32 v64, v64, v22, v23
	v_max3_f32 v64, v64, v24, v25
	v_max3_f32 v64, v64, v26, v27
	v_max3_f32 v64, v64, v28, v29
	v_max3_f32 v64, v64, v30, v31
	v_mov_b32_e32 v65, v64
	s_nop 1
	v_permlane32_swap_b32_e32 v64, v65
	v_max_f32_e32 v65, v65, v65
	v_max_f32_e32 v64, v64, v64
	v_max_f32_e32 v80, v64, v65
	v_add_f32_e32 v213, 0, v80
	v_xor_b32_e32 v64, 0x80000000, v213
	v_sub_f32_e32 v32, v32, v80
	v_sub_f32_e32 v33, v33, v80
	v_sub_f32_e32 v34, v34, v80
	v_sub_f32_e32 v35, v35, v80
	v_sub_f32_e32 v36, v36, v80
	v_sub_f32_e32 v37, v37, v80
	v_sub_f32_e32 v38, v38, v80
	v_sub_f32_e32 v39, v39, v80
	v_sub_f32_e32 v40, v40, v80
	v_sub_f32_e32 v41, v41, v80
	v_sub_f32_e32 v42, v42, v80
	v_sub_f32_e32 v43, v43, v80
	v_sub_f32_e32 v44, v44, v80
	v_sub_f32_e32 v45, v45, v80
	v_sub_f32_e32 v46, v46, v80
	v_sub_f32_e32 v47, v47, v80
	v_mov_b32_e32 v65, v64
	v_mov_b32_e32 v66, v64
	v_mov_b32_e32 v67, v64
	v_mov_b32_e32 v68, v64
	v_mov_b32_e32 v69, v64
	v_mov_b32_e32 v70, v64
	v_mov_b32_e32 v71, v64
	v_mov_b32_e32 v72, v64
	v_mov_b32_e32 v73, v64
	v_mov_b32_e32 v74, v64
	v_mov_b32_e32 v75, v64
	v_mov_b32_e32 v76, v64
	v_mov_b32_e32 v77, v64
	v_mov_b32_e32 v78, v64
	v_mov_b32_e32 v79, v64
	v_exp_f32_e32 v98, v32
	v_exp_f32_e32 v99, v33
	v_exp_f32_e32 v34, v34
	v_exp_f32_e32 v35, v35
	v_exp_f32_e32 v36, v36
	v_exp_f32_e32 v37, v37
	v_exp_f32_e32 v38, v38
	v_exp_f32_e32 v39, v39
	v_exp_f32_e32 v40, v40
	v_exp_f32_e32 v41, v41
	v_exp_f32_e32 v42, v42
	v_exp_f32_e32 v43, v43
	v_exp_f32_e32 v44, v44
	v_exp_f32_e32 v45, v45
	v_exp_f32_e32 v46, v46
	v_exp_f32_e32 v47, v47
	v_cvt_pk_bf16_f32 v180, v98, v99
	v_cvt_pk_bf16_f32 v181, v34, v35
	v_cvt_pk_bf16_f32 v182, v36, v37
	v_cvt_pk_bf16_f32 v183, v38, v39
	v_cvt_pk_bf16_f32 v176, v40, v41
	v_cvt_pk_bf16_f32 v177, v42, v43
	v_cvt_pk_bf16_f32 v178, v44, v45
	v_cvt_pk_bf16_f32 v179, v46, v47
	s_waitcnt vmcnt(5) lgkmcnt(0)
	s_barrier
	v_lshl_add_u64 v[32:33], v[52:53], 0, s[36:37]
	s_mov_b64 s[36:37], 0xe0000
	global_load_lds_dwordx4 v[32:33], off
	v_lshl_add_u64 v[32:33], v[52:53], 0, s[36:37]
	s_mov_b32 m0, s25
	s_mov_b64 s[36:37], 0x6000
	global_load_lds_dwordx4 v[32:33], off
	v_lshl_add_u64 v[32:33], v[54:55], 0, s[36:37]
	s_mov_b32 m0, s14
	s_mov_b64 s[14:15], 0x80100
	global_load_lds_dwordx4 v[32:33], off
	v_lshl_add_u64 v[32:33], v[56:57], 0, s[14:15]
	s_add_i32 m0, s20, 0x1a000
	s_mov_b64 s[14:15], 0xa0100
	global_load_lds_dwordx4 v[32:33], off
	v_lshl_add_u64 v[32:33], v[56:57], 0, s[14:15]
	s_add_i32 m0, s20, 0x1c000
	v_sub_f32_e32 v95, v31, v80
	global_load_lds_dwordx4 v[32:33], off
	v_sub_f32_e32 v94, v30, v80
	v_sub_f32_e32 v93, v29, v80
	v_sub_f32_e32 v92, v28, v80
	v_sub_f32_e32 v91, v27, v80
	v_sub_f32_e32 v90, v26, v80
	v_sub_f32_e32 v89, v25, v80
	v_sub_f32_e32 v88, v24, v80
	v_sub_f32_e32 v87, v23, v80
	v_sub_f32_e32 v86, v22, v80
	v_sub_f32_e32 v85, v21, v80
	v_sub_f32_e32 v84, v20, v80
	v_sub_f32_e32 v83, v19, v80
	v_sub_f32_e32 v82, v18, v80
	v_sub_f32_e32 v81, v17, v80
	v_sub_f32_e32 v80, v16, v80
	v_add_f32_e32 v16, 0, v98
	v_add_f32_e32 v16, v99, v16
	v_add_f32_e32 v16, v34, v16
	v_add_f32_e32 v16, v35, v16
	v_add_f32_e32 v16, v36, v16
	v_add_f32_e32 v16, v37, v16
	v_add_f32_e32 v16, v38, v16
	v_add_f32_e32 v16, v39, v16
	v_add_f32_e32 v16, v40, v16
	v_add_f32_e32 v16, v41, v16
	v_add_f32_e32 v16, v42, v16
	v_add_f32_e32 v16, v43, v16
	v_add_f32_e32 v16, v44, v16
	v_add_f32_e32 v16, v45, v16
	v_add_f32_e32 v16, v46, v16
	v_add_f32_e32 v200, v47, v16
	v_or3_b32 v16, v63, v62, v59
	v_lshlrev_b32_e32 v16, 11, v16
	s_add_u32 s6, s6, s8
	v_or3_b32 v16, v16, v60, v61
	v_or_b32_e32 v32, 64, v184
	v_or_b32_e32 v33, 0x60, v184
	v_or_b32_e32 v52, 0x80, v184
	v_or_b32_e32 v53, 0xa0, v184
	v_or_b32_e32 v54, 0xc0, v184
	v_or_b32_e32 v55, 0xe0, v184
	s_addc_u32 s7, s7, s9
	v_ashrrev_i32_e32 v17, 31, v16
	v_bitop3_b32 v226, v32, v218, v96 bitop3:0xde
	v_bitop3_b32 v227, v33, v218, v96 bitop3:0xde
	v_bitop3_b32 v228, v52, v218, v96 bitop3:0xde
	v_bitop3_b32 v229, v53, v218, v96 bitop3:0xde
	v_bitop3_b32 v230, v54, v218, v96 bitop3:0xde
	v_bitop3_b32 v231, v55, v218, v96 bitop3:0xde
	v_bitop3_b32 v234, v32, v219, v96 bitop3:0xde
	v_bitop3_b32 v235, v33, v219, v96 bitop3:0xde
	v_cmp_gt_u32_e64 s[36:37], 32, v58
	v_lshl_add_u64 v[196:197], s[6:7], 0, v[48:49]
	v_lshl_add_u64 v[198:199], v[16:17], 1, s[6:7]
	v_mov_b64_e32 v[62:63], v[14:15]
	v_mov_b64_e32 v[46:47], v[14:15]
	v_mov_b64_e32 v[30:31], v[14:15]
	v_permlane32_swap_b32_e32 v180, v182
	v_permlane32_swap_b32_e32 v181, v183
	v_permlane32_swap_b32_e32 v176, v178
	v_permlane32_swap_b32_e32 v177, v179
	v_sub_u32_e32 v238, v226, v219
	v_sub_u32_e32 v239, v227, v219
	v_mov_b64_e32 v[60:61], v[12:13]
	v_mov_b64_e32 v[58:59], v[10:11]
	v_mov_b64_e32 v[56:57], v[8:9]
	v_mov_b64_e32 v[54:55], v[6:7]
	v_mov_b64_e32 v[52:53], v[4:5]
	v_mov_b64_e32 v[50:51], v[2:3]
	v_mov_b64_e32 v[48:49], v[0:1]
	v_mov_b64_e32 v[44:45], v[12:13]
	v_mov_b64_e32 v[42:43], v[10:11]
	v_mov_b64_e32 v[40:41], v[8:9]
	v_mov_b64_e32 v[38:39], v[6:7]
	v_mov_b64_e32 v[36:37], v[4:5]
	v_mov_b64_e32 v[34:35], v[2:3]
	v_mov_b64_e32 v[32:33], v[0:1]
	v_mov_b64_e32 v[28:29], v[12:13]
	v_mov_b64_e32 v[26:27], v[10:11]
	v_mov_b64_e32 v[24:25], v[8:9]
	v_mov_b64_e32 v[22:23], v[6:7]
	v_mov_b64_e32 v[20:21], v[4:5]
	v_mov_b64_e32 v[18:19], v[2:3]
	v_mov_b64_e32 v[16:17], v[0:1]
	s_mov_b32 s14, 1
	.p2align	6

; template <class Epi, bool ALIGN_EPI>
; __device__ __forceinline__ void gemm_phase(LAS unsigned char* lds, const Gemm g, const StaticOrder& S, const Epi& E, const int wave_s) {
;     ...
;         float zz1; asm volatile("v_mov_b32 %0, 0" : "=v"(zz1));
; #pragma unroll
;         for (int a = 0; a < 2; ++a)
; #pragma unroll
;             for (int b = 0; b < 2; ++b)
; #pragma unroll
;                 for (int m = 0; m < 4; ++m)
; #pragma unroll
;                     for (int n = 0; n < 2; ++n) acc[a][b][m][n] = (f32x4){zz1, zz1, zz1, zz1};
;         cur = nxt; cA = nA; cB = nB; ++ui;
.LBB0_539:
	s_add_u32 s67, s38, 0x100
	s_addc_u32 s68, s39, 0
	s_add_u32 s38, s50, 0x80
	v_mov_b64_e32 v[6:7], v[2:3]
	v_mov_b64_e32 v[10:11], v[2:3]
	v_mov_b64_e32 v[14:15], v[2:3]
	v_mov_b64_e32 v[18:19], v[2:3]
	v_mov_b64_e32 v[22:23], v[2:3]
	v_mov_b64_e32 v[26:27], v[2:3]
	v_mov_b64_e32 v[30:31], v[2:3]
	v_mov_b64_e32 v[66:67], v[2:3]
	v_mov_b64_e32 v[70:71], v[2:3]
	v_mov_b64_e32 v[74:75], v[2:3]
	v_mov_b64_e32 v[78:79], v[2:3]
	v_mov_b64_e32 v[82:83], v[2:3]
	v_mov_b64_e32 v[86:87], v[2:3]
	v_mov_b64_e32 v[90:91], v[2:3]
	v_mov_b64_e32 v[94:95], v[2:3]
	v_mov_b64_e32 v[34:35], v[2:3]
	v_mov_b64_e32 v[38:39], v[2:3]
	v_mov_b64_e32 v[42:43], v[2:3]
	v_mov_b64_e32 v[46:47], v[2:3]
	v_mov_b64_e32 v[50:51], v[2:3]
	v_mov_b64_e32 v[54:55], v[2:3]
	v_mov_b64_e32 v[58:59], v[2:3]
	v_mov_b64_e32 v[62:63], v[2:3]
	v_mov_b64_e32 v[98:99], v[2:3]
	v_mov_b64_e32 v[102:103], v[2:3]
	v_mov_b64_e32 v[106:107], v[2:3]
	v_mov_b64_e32 v[110:111], v[2:3]
	v_mov_b64_e32 v[114:115], v[2:3]
	v_mov_b64_e32 v[118:119], v[2:3]
	v_mov_b64_e32 v[122:123], v[2:3]
	v_mov_b64_e32 v[126:127], v[2:3]
	s_addc_u32 s39, s51, 0
	s_mov_b32 s50, 0
	v_mov_b64_e32 v[4:5], v[0:1]
	v_mov_b64_e32 v[8:9], v[0:1]
	v_mov_b64_e32 v[12:13], v[0:1]
	v_mov_b64_e32 v[16:17], v[0:1]
	v_mov_b64_e32 v[20:21], v[0:1]
	v_mov_b64_e32 v[24:25], v[0:1]
	v_mov_b64_e32 v[28:29], v[0:1]
	v_mov_b64_e32 v[64:65], v[0:1]
	v_mov_b64_e32 v[68:69], v[0:1]
	v_mov_b64_e32 v[72:73], v[0:1]
	v_mov_b64_e32 v[76:77], v[0:1]
	v_mov_b64_e32 v[80:81], v[0:1]
	v_mov_b64_e32 v[84:85], v[0:1]
	v_mov_b64_e32 v[88:89], v[0:1]
	v_mov_b64_e32 v[92:93], v[0:1]
	v_mov_b64_e32 v[32:33], v[0:1]
	v_mov_b64_e32 v[36:37], v[0:1]
	v_mov_b64_e32 v[40:41], v[0:1]
	v_mov_b64_e32 v[44:45], v[0:1]
	v_mov_b64_e32 v[48:49], v[0:1]
	v_mov_b64_e32 v[52:53], v[0:1]
	v_mov_b64_e32 v[56:57], v[0:1]
	v_mov_b64_e32 v[60:61], v[0:1]
	v_mov_b64_e32 v[96:97], v[0:1]
	v_mov_b64_e32 v[100:101], v[0:1]
	v_mov_b64_e32 v[104:105], v[0:1]
	v_mov_b64_e32 v[108:109], v[0:1]
	v_mov_b64_e32 v[112:113], v[0:1]
	v_mov_b64_e32 v[116:117], v[0:1]
	v_mov_b64_e32 v[120:121], v[0:1]
	v_mov_b64_e32 v[124:125], v[0:1]
	.p2align	6

; template <class Epi, bool ALIGN_EPI>
; __device__ __forceinline__ void gemm_phase(LAS unsigned char* lds, const Gemm g, const StaticOrder& S, const Epi& E, const int wave_s) {
;     ...
;         float zz1; asm volatile("v_mov_b32 %0, 0" : "=v"(zz1));
; #pragma unroll
;         for (int a = 0; a < 2; ++a)
; #pragma unroll
;             for (int b = 0; b < 2; ++b)
; #pragma unroll
;                 for (int m = 0; m < 4; ++m)
; #pragma unroll
;                     for (int n = 0; n < 2; ++n) acc[a][b][m][n] = (f32x4){zz1, zz1, zz1, zz1};
;         cur = nxt; cA = nA; cB = nB; ++ui;
.LBB0_597:
	s_add_u32 s61, s38, 0x100
	s_addc_u32 s63, s39, 0
	s_add_u32 s38, s46, 0x80
	v_mov_b64_e32 v[6:7], v[2:3]
	v_mov_b64_e32 v[18:19], v[2:3]
	v_mov_b64_e32 v[22:23], v[2:3]
	v_mov_b64_e32 v[34:35], v[2:3]
	v_mov_b64_e32 v[38:39], v[2:3]
	v_mov_b64_e32 v[50:51], v[2:3]
	v_mov_b64_e32 v[54:55], v[2:3]
	v_mov_b64_e32 v[10:11], v[2:3]
	v_mov_b64_e32 v[14:15], v[2:3]
	v_mov_b64_e32 v[26:27], v[2:3]
	v_mov_b64_e32 v[30:31], v[2:3]
	v_mov_b64_e32 v[42:43], v[2:3]
	v_mov_b64_e32 v[46:47], v[2:3]
	v_mov_b64_e32 v[58:59], v[2:3]
	v_mov_b64_e32 v[62:63], v[2:3]
	v_mov_b64_e32 v[66:67], v[2:3]
	v_mov_b64_e32 v[70:71], v[2:3]
	v_mov_b64_e32 v[82:83], v[2:3]
	v_mov_b64_e32 v[86:87], v[2:3]
	v_mov_b64_e32 v[98:99], v[2:3]
	v_mov_b64_e32 v[102:103], v[2:3]
	v_mov_b64_e32 v[114:115], v[2:3]
	v_mov_b64_e32 v[118:119], v[2:3]
	v_mov_b64_e32 v[74:75], v[2:3]
	v_mov_b64_e32 v[78:79], v[2:3]
	v_mov_b64_e32 v[90:91], v[2:3]
	v_mov_b64_e32 v[94:95], v[2:3]
	v_mov_b64_e32 v[106:107], v[2:3]
	v_mov_b64_e32 v[110:111], v[2:3]
	v_mov_b64_e32 v[122:123], v[2:3]
	v_mov_b64_e32 v[126:127], v[2:3]
	s_addc_u32 s39, s47, 0
	s_mov_b32 s46, 0
	v_mov_b64_e32 v[4:5], v[0:1]
	v_mov_b64_e32 v[16:17], v[0:1]
	v_mov_b64_e32 v[20:21], v[0:1]
	v_mov_b64_e32 v[32:33], v[0:1]
	v_mov_b64_e32 v[36:37], v[0:1]
	v_mov_b64_e32 v[48:49], v[0:1]
	v_mov_b64_e32 v[52:53], v[0:1]
	v_mov_b64_e32 v[8:9], v[0:1]
	v_mov_b64_e32 v[12:13], v[0:1]
	v_mov_b64_e32 v[24:25], v[0:1]
	v_mov_b64_e32 v[28:29], v[0:1]
	v_mov_b64_e32 v[40:41], v[0:1]
	v_mov_b64_e32 v[44:45], v[0:1]
	v_mov_b64_e32 v[56:57], v[0:1]
	v_mov_b64_e32 v[60:61], v[0:1]
	v_mov_b64_e32 v[64:65], v[0:1]
	v_mov_b64_e32 v[68:69], v[0:1]
	v_mov_b64_e32 v[80:81], v[0:1]
	v_mov_b64_e32 v[84:85], v[0:1]
	v_mov_b64_e32 v[96:97], v[0:1]
	v_mov_b64_e32 v[100:101], v[0:1]
	v_mov_b64_e32 v[112:113], v[0:1]
	v_mov_b64_e32 v[116:117], v[0:1]
	v_mov_b64_e32 v[72:73], v[0:1]
	v_mov_b64_e32 v[76:77], v[0:1]
	v_mov_b64_e32 v[88:89], v[0:1]
	v_mov_b64_e32 v[92:93], v[0:1]
	v_mov_b64_e32 v[104:105], v[0:1]
	v_mov_b64_e32 v[108:109], v[0:1]
	v_mov_b64_e32 v[120:121], v[0:1]
	v_mov_b64_e32 v[124:125], v[0:1]
	.p2align	6

; template <class Epi, bool ALIGN_EPI>
; __device__ __forceinline__ void gemm_phase(LAS unsigned char* lds, const Gemm g, const StaticOrder& S, const Epi& E, const int wave_s) {
;     ...
;         float zz1; asm volatile("v_mov_b32 %0, 0" : "=v"(zz1));
; #pragma unroll
;         for (int a = 0; a < 2; ++a)
; #pragma unroll
;             for (int b = 0; b < 2; ++b)
; #pragma unroll
;                 for (int m = 0; m < 4; ++m)
; #pragma unroll
;                     for (int n = 0; n < 2; ++n) acc[a][b][m][n] = (f32x4){zz1, zz1, zz1, zz1};
;         cur = nxt; cA = nA; cB = nB; ++ui;
.LBB0_640:
	s_add_u32 s57, s38, 0x100
	s_addc_u32 s58, s39, 0
	s_add_u32 s38, s40, 0x80
	v_mov_b64_e32 v[6:7], v[2:3]
	v_mov_b64_e32 v[18:19], v[2:3]
	v_mov_b64_e32 v[22:23], v[2:3]
	v_mov_b64_e32 v[34:35], v[2:3]
	v_mov_b64_e32 v[38:39], v[2:3]
	v_mov_b64_e32 v[50:51], v[2:3]
	v_mov_b64_e32 v[54:55], v[2:3]
	v_mov_b64_e32 v[10:11], v[2:3]
	v_mov_b64_e32 v[14:15], v[2:3]
	v_mov_b64_e32 v[26:27], v[2:3]
	v_mov_b64_e32 v[30:31], v[2:3]
	v_mov_b64_e32 v[42:43], v[2:3]
	v_mov_b64_e32 v[46:47], v[2:3]
	v_mov_b64_e32 v[58:59], v[2:3]
	v_mov_b64_e32 v[62:63], v[2:3]
	v_mov_b64_e32 v[66:67], v[2:3]
	v_mov_b64_e32 v[70:71], v[2:3]
	v_mov_b64_e32 v[82:83], v[2:3]
	v_mov_b64_e32 v[86:87], v[2:3]
	v_mov_b64_e32 v[98:99], v[2:3]
	v_mov_b64_e32 v[102:103], v[2:3]
	v_mov_b64_e32 v[114:115], v[2:3]
	v_mov_b64_e32 v[118:119], v[2:3]
	v_mov_b64_e32 v[74:75], v[2:3]
	v_mov_b64_e32 v[78:79], v[2:3]
	v_mov_b64_e32 v[90:91], v[2:3]
	v_mov_b64_e32 v[94:95], v[2:3]
	v_mov_b64_e32 v[106:107], v[2:3]
	v_mov_b64_e32 v[110:111], v[2:3]
	v_mov_b64_e32 v[122:123], v[2:3]
	v_mov_b64_e32 v[126:127], v[2:3]
	s_addc_u32 s39, s41, 0
	s_mov_b32 s40, 0
	v_mov_b64_e32 v[4:5], v[0:1]
	v_mov_b64_e32 v[16:17], v[0:1]
	v_mov_b64_e32 v[20:21], v[0:1]
	v_mov_b64_e32 v[32:33], v[0:1]
	v_mov_b64_e32 v[36:37], v[0:1]
	v_mov_b64_e32 v[48:49], v[0:1]
	v_mov_b64_e32 v[52:53], v[0:1]
	v_mov_b64_e32 v[8:9], v[0:1]
	v_mov_b64_e32 v[12:13], v[0:1]
	v_mov_b64_e32 v[24:25], v[0:1]
	v_mov_b64_e32 v[28:29], v[0:1]
	v_mov_b64_e32 v[40:41], v[0:1]
	v_mov_b64_e32 v[44:45], v[0:1]
	v_mov_b64_e32 v[56:57], v[0:1]
	v_mov_b64_e32 v[60:61], v[0:1]
	v_mov_b64_e32 v[64:65], v[0:1]
	v_mov_b64_e32 v[68:69], v[0:1]
	v_mov_b64_e32 v[80:81], v[0:1]
	v_mov_b64_e32 v[84:85], v[0:1]
	v_mov_b64_e32 v[96:97], v[0:1]
	v_mov_b64_e32 v[100:101], v[0:1]
	v_mov_b64_e32 v[112:113], v[0:1]
	v_mov_b64_e32 v[116:117], v[0:1]
	v_mov_b64_e32 v[72:73], v[0:1]
	v_mov_b64_e32 v[76:77], v[0:1]
	v_mov_b64_e32 v[88:89], v[0:1]
	v_mov_b64_e32 v[92:93], v[0:1]
	v_mov_b64_e32 v[104:105], v[0:1]
	v_mov_b64_e32 v[108:109], v[0:1]
	v_mov_b64_e32 v[120:121], v[0:1]
	v_mov_b64_e32 v[124:125], v[0:1]
	.p2align	6

; template <class Epi, bool ALIGN_EPI>
; __device__ __forceinline__ void gemm_phase(LAS unsigned char* lds, const Gemm g, const StaticOrder& S, const Epi& E, const int wave_s) {
;     ...
;         float zz1; asm volatile("v_mov_b32 %0, 0" : "=v"(zz1));
; #pragma unroll
;         for (int a = 0; a < 2; ++a)
; #pragma unroll
;             for (int b = 0; b < 2; ++b)
; #pragma unroll
;                 for (int m = 0; m < 4; ++m)
; #pragma unroll
;                     for (int n = 0; n < 2; ++n) acc[a][b][m][n] = (f32x4){zz1, zz1, zz1, zz1};
;         cur = nxt; cA = nA; cB = nB; ++ui;
.LBB0_887:
	s_add_u32 s55, s40, 0x100
	s_addc_u32 s56, s41, 0
	s_add_u32 s40, s42, 0x80
	s_waitcnt lgkmcnt(0)
	v_mov_b64_e32 v[6:7], v[2:3]
	v_mov_b64_e32 v[18:19], v[2:3]
	v_mov_b64_e32 v[22:23], v[2:3]
	v_mov_b64_e32 v[50:51], v[2:3]
	v_mov_b64_e32 v[54:55], v[2:3]
	v_mov_b64_e32 v[66:67], v[2:3]
	v_mov_b64_e32 v[70:71], v[2:3]
	v_mov_b64_e32 v[10:11], v[2:3]
	v_mov_b64_e32 v[14:15], v[2:3]
	v_mov_b64_e32 v[34:35], v[2:3]
	v_mov_b64_e32 v[38:39], v[2:3]
	v_mov_b64_e32 v[58:59], v[2:3]
	v_mov_b64_e32 v[62:63], v[2:3]
	v_mov_b64_e32 v[74:75], v[2:3]
	v_mov_b64_e32 v[78:79], v[2:3]
	v_mov_b64_e32 v[82:83], v[2:3]
	v_mov_b64_e32 v[86:87], v[2:3]
	v_mov_b64_e32 v[98:99], v[2:3]
	v_mov_b64_e32 v[102:103], v[2:3]
	v_mov_b64_e32 v[114:115], v[2:3]
	v_mov_b64_e32 v[118:119], v[2:3]
	v_mov_b64_e32 v[130:131], v[2:3]
	v_mov_b64_e32 v[134:135], v[2:3]
	v_mov_b64_e32 v[90:91], v[2:3]
	v_mov_b64_e32 v[94:95], v[2:3]
	v_mov_b64_e32 v[106:107], v[2:3]
	v_mov_b64_e32 v[110:111], v[2:3]
	v_mov_b64_e32 v[122:123], v[2:3]
	v_mov_b64_e32 v[126:127], v[2:3]
	v_mov_b64_e32 v[138:139], v[2:3]
	v_mov_b64_e32 v[142:143], v[2:3]
	s_addc_u32 s41, s43, 0
	s_mov_b32 s42, 0
	v_mov_b64_e32 v[4:5], v[0:1]
	v_mov_b64_e32 v[16:17], v[0:1]
	v_mov_b64_e32 v[20:21], v[0:1]
	v_mov_b64_e32 v[48:49], v[0:1]
	v_mov_b64_e32 v[52:53], v[0:1]
	v_mov_b64_e32 v[64:65], v[0:1]
	v_mov_b64_e32 v[68:69], v[0:1]
	v_mov_b64_e32 v[8:9], v[0:1]
	v_mov_b64_e32 v[12:13], v[0:1]
	v_mov_b64_e32 v[32:33], v[0:1]
	v_mov_b64_e32 v[36:37], v[0:1]
	v_mov_b64_e32 v[56:57], v[0:1]
	v_mov_b64_e32 v[60:61], v[0:1]
	v_mov_b64_e32 v[72:73], v[0:1]
	v_mov_b64_e32 v[76:77], v[0:1]
	v_mov_b64_e32 v[80:81], v[0:1]
	v_mov_b64_e32 v[84:85], v[0:1]
	v_mov_b64_e32 v[96:97], v[0:1]
	v_mov_b64_e32 v[100:101], v[0:1]
	v_mov_b64_e32 v[112:113], v[0:1]
	v_mov_b64_e32 v[116:117], v[0:1]
	v_mov_b64_e32 v[128:129], v[0:1]
	v_mov_b64_e32 v[132:133], v[0:1]
	v_mov_b64_e32 v[88:89], v[0:1]
	v_mov_b64_e32 v[92:93], v[0:1]
	v_mov_b64_e32 v[104:105], v[0:1]
	v_mov_b64_e32 v[108:109], v[0:1]
	v_mov_b64_e32 v[120:121], v[0:1]
	v_mov_b64_e32 v[124:125], v[0:1]
	v_mov_b64_e32 v[136:137], v[0:1]
	v_mov_b64_e32 v[140:141], v[0:1]
	.p2align	6
